# attention: Q-tile staging and rotary loops unrolled with all loads in flight; softmax row max on raw scores + permlane32_swap instead of ds_bpermute
# speedup vs baseline: 1.0510x; 1.0067x over previous
; template <int DK, int DV, int KT, bool SAMPLE>
; DI void attn_item(CP c, int l, int qb, int h, unsigned char* sm) {
;     ...
;     if (!SAMPLE) {
;         for (int v = tid; v < 128 * 24; v += 512) { const int r = v / 24, s = v % 24; *(u32x4*)(Qs + r * QS + s * 8) = *(const u32x4*)(Qg + (size_t)(qb * 128 + r) * 768 + h * 192 + s * 8); }
.LBB0_641:
	v_mul_hi_i32 v8, v7, s68
	v_lshrrev_b32_e32 v9, 31, v8
	v_ashrrev_i32_e32 v8, 2, v8
	v_add_u32_e32 v12, v8, v9
	s_movk_i32 s14, 0xff40
	v_add_u32_e32 v10, v12, v153
	v_mad_u64_u32 v[8:9], s[18:19], v12, s14, v[0:1]
	v_mad_i64_i32 v[10:11], s[18:19], v10, s69, v[2:3]
	v_ashrrev_i32_e32 v9, 31, v8
	v_lshl_add_u64 v[8:9], v[8:9], 1, v[10:11]
	global_load_dwordx4 v[16:19], v[8:9], off
	v_add_u32_e32 v7, 0x200, v7
	v_lshl_add_u32 v40, v12, 4, v6
	v_add_u32_e32 v6, 0x2000, v6
	v_add_u32_e32 v0, 0x1000, v0
	v_mul_hi_i32 v8, v7, s68
	v_lshrrev_b32_e32 v9, 31, v8
	v_ashrrev_i32_e32 v8, 2, v8
	v_add_u32_e32 v12, v8, v9
	s_movk_i32 s14, 0xff40
	v_add_u32_e32 v10, v12, v153
	v_mad_u64_u32 v[8:9], s[18:19], v12, s14, v[0:1]
	v_mad_i64_i32 v[10:11], s[18:19], v10, s69, v[2:3]
	v_ashrrev_i32_e32 v9, 31, v8
	v_lshl_add_u64 v[8:9], v[8:9], 1, v[10:11]
	global_load_dwordx4 v[20:23], v[8:9], off
	v_add_u32_e32 v7, 0x200, v7
	v_lshl_add_u32 v41, v12, 4, v6
	v_add_u32_e32 v6, 0x2000, v6
	v_add_u32_e32 v0, 0x1000, v0
	v_mul_hi_i32 v8, v7, s68
	v_lshrrev_b32_e32 v9, 31, v8
	v_ashrrev_i32_e32 v8, 2, v8
	v_add_u32_e32 v12, v8, v9
	s_movk_i32 s14, 0xff40
	v_add_u32_e32 v10, v12, v153
	v_mad_u64_u32 v[8:9], s[18:19], v12, s14, v[0:1]
	v_mad_i64_i32 v[10:11], s[18:19], v10, s69, v[2:3]
	v_ashrrev_i32_e32 v9, 31, v8
	v_lshl_add_u64 v[8:9], v[8:9], 1, v[10:11]
	global_load_dwordx4 v[24:27], v[8:9], off
	v_add_u32_e32 v7, 0x200, v7
	v_lshl_add_u32 v42, v12, 4, v6
	v_add_u32_e32 v6, 0x2000, v6
	v_add_u32_e32 v0, 0x1000, v0
	v_mul_hi_i32 v8, v7, s68
	v_lshrrev_b32_e32 v9, 31, v8
	v_ashrrev_i32_e32 v8, 2, v8
	v_add_u32_e32 v12, v8, v9
	s_movk_i32 s14, 0xff40
	v_add_u32_e32 v10, v12, v153
	v_mad_u64_u32 v[8:9], s[18:19], v12, s14, v[0:1]
	v_mad_i64_i32 v[10:11], s[18:19], v10, s69, v[2:3]
	v_ashrrev_i32_e32 v9, 31, v8
	v_lshl_add_u64 v[8:9], v[8:9], 1, v[10:11]
	global_load_dwordx4 v[28:31], v[8:9], off
	v_add_u32_e32 v7, 0x200, v7
	v_lshl_add_u32 v43, v12, 4, v6
	v_add_u32_e32 v6, 0x2000, v6
	v_add_u32_e32 v0, 0x1000, v0
	v_mul_hi_i32 v8, v7, s68
	v_lshrrev_b32_e32 v9, 31, v8
	v_ashrrev_i32_e32 v8, 2, v8
	v_add_u32_e32 v12, v8, v9
	s_movk_i32 s14, 0xff40
	v_add_u32_e32 v10, v12, v153
	v_mad_u64_u32 v[8:9], s[18:19], v12, s14, v[0:1]
	v_mad_i64_i32 v[10:11], s[18:19], v10, s69, v[2:3]
	v_ashrrev_i32_e32 v9, 31, v8
	v_lshl_add_u64 v[8:9], v[8:9], 1, v[10:11]
	global_load_dwordx4 v[32:35], v[8:9], off
	v_add_u32_e32 v7, 0x200, v7
	v_lshl_add_u32 v44, v12, 4, v6
	v_add_u32_e32 v6, 0x2000, v6
	v_add_u32_e32 v0, 0x1000, v0
	v_mul_hi_i32 v8, v7, s68
	v_lshrrev_b32_e32 v9, 31, v8
	v_ashrrev_i32_e32 v8, 2, v8
	v_add_u32_e32 v12, v8, v9
	s_movk_i32 s14, 0xff40
	v_add_u32_e32 v10, v12, v153
	v_mad_u64_u32 v[8:9], s[18:19], v12, s14, v[0:1]
	v_mad_i64_i32 v[10:11], s[18:19], v10, s69, v[2:3]
	v_ashrrev_i32_e32 v9, 31, v8
	v_lshl_add_u64 v[8:9], v[8:9], 1, v[10:11]
	global_load_dwordx4 v[36:39], v[8:9], off
	v_add_u32_e32 v7, 0x200, v7
	v_lshl_add_u32 v45, v12, 4, v6
	v_add_u32_e32 v6, 0x2000, v6
	v_add_u32_e32 v0, 0x1000, v0
	s_waitcnt vmcnt(0)
	ds_write_b128 v40, v[16:19]
	ds_write_b128 v41, v[20:23]
	ds_write_b128 v42, v[24:27]
	ds_write_b128 v43, v[28:31]
	ds_write_b128 v44, v[32:35]
	ds_write_b128 v45, v[36:39]

; DI float bf2f(bf16_t b) { return __uint_as_float(((unsigned)b) << 16); }
; DI bf16_t f2bf(float f) { unsigned u = __float_as_uint(f); u += 0x7FFFu + ((u >> 16) & 1u); return (bf16_t)(u >> 16); }
; template <int DK, int DV, int KT, bool SAMPLE>
; DI void attn_item(CP c, int l, int qb, int h, unsigned char* sm) {
;     ...
;     for (int v = tid; v < NQ * 32; v += 512) { const int r = v >> 5, f = v & 31; const int pos = SAMPLE ? 2048 + (r & 15) : qb * 128 + r;
;         const float co = rope[((size_t)pos * 32 + f) * 2], si = rope[((size_t)pos * 32 + f) * 2 + 1];
;         bf16_t* q = Qs + r * QS + (DK - 64); const float x1 = bf2f(q[f]), x2 = bf2f(q[32 + f]);
;         q[f] = f2bf(x1 * co - x2 * si); q[32 + f] = f2bf(x2 * co + x1 * si); }
.LBB0_644:
	v_ashrrev_i32_e32 v7, 5, v6
	v_add_u32_e32 v8, v7, v153
	v_ashrrev_i32_e32 v9, 31, v8
	v_lshlrev_b64 v[8:9], 8, v[8:9]
	v_lshl_add_u64 v[8:9], v[2:3], 0, v[8:9]
	global_load_dwordx2 v[16:17], v[8:9], off
	v_mad_u64_u32 v[10:11], s[18:19], v7, s14, v[0:1]
	v_mov_b32_e32 v48, v10
	ds_read_u16 v32, v10 offset:256
	ds_read_u16 v40, v10 offset:320
	v_add_u32_e32 v6, 0x200, v6
	v_ashrrev_i32_e32 v7, 5, v6
	v_add_u32_e32 v8, v7, v153
	v_ashrrev_i32_e32 v9, 31, v8
	v_lshlrev_b64 v[8:9], 8, v[8:9]
	v_lshl_add_u64 v[8:9], v[2:3], 0, v[8:9]
	global_load_dwordx2 v[18:19], v[8:9], off
	v_mad_u64_u32 v[10:11], s[18:19], v7, s14, v[0:1]
	v_mov_b32_e32 v49, v10
	ds_read_u16 v33, v10 offset:256
	ds_read_u16 v41, v10 offset:320
	v_add_u32_e32 v6, 0x200, v6
	v_ashrrev_i32_e32 v7, 5, v6
	v_add_u32_e32 v8, v7, v153
	v_ashrrev_i32_e32 v9, 31, v8
	v_lshlrev_b64 v[8:9], 8, v[8:9]
	v_lshl_add_u64 v[8:9], v[2:3], 0, v[8:9]
	global_load_dwordx2 v[20:21], v[8:9], off
	v_mad_u64_u32 v[10:11], s[18:19], v7, s14, v[0:1]
	v_mov_b32_e32 v50, v10
	ds_read_u16 v34, v10 offset:256
	ds_read_u16 v42, v10 offset:320
	v_add_u32_e32 v6, 0x200, v6
	v_ashrrev_i32_e32 v7, 5, v6
	v_add_u32_e32 v8, v7, v153
	v_ashrrev_i32_e32 v9, 31, v8
	v_lshlrev_b64 v[8:9], 8, v[8:9]
	v_lshl_add_u64 v[8:9], v[2:3], 0, v[8:9]
	global_load_dwordx2 v[22:23], v[8:9], off
	v_mad_u64_u32 v[10:11], s[18:19], v7, s14, v[0:1]
	v_mov_b32_e32 v51, v10
	ds_read_u16 v35, v10 offset:256
	ds_read_u16 v43, v10 offset:320
	v_add_u32_e32 v6, 0x200, v6
	v_ashrrev_i32_e32 v7, 5, v6
	v_add_u32_e32 v8, v7, v153
	v_ashrrev_i32_e32 v9, 31, v8
	v_lshlrev_b64 v[8:9], 8, v[8:9]
	v_lshl_add_u64 v[8:9], v[2:3], 0, v[8:9]
	global_load_dwordx2 v[24:25], v[8:9], off
	v_mad_u64_u32 v[10:11], s[18:19], v7, s14, v[0:1]
	v_mov_b32_e32 v52, v10
	ds_read_u16 v36, v10 offset:256
	ds_read_u16 v44, v10 offset:320
	v_add_u32_e32 v6, 0x200, v6
	v_ashrrev_i32_e32 v7, 5, v6
	v_add_u32_e32 v8, v7, v153
	v_ashrrev_i32_e32 v9, 31, v8
	v_lshlrev_b64 v[8:9], 8, v[8:9]
	v_lshl_add_u64 v[8:9], v[2:3], 0, v[8:9]
	global_load_dwordx2 v[26:27], v[8:9], off
	v_mad_u64_u32 v[10:11], s[18:19], v7, s14, v[0:1]
	v_mov_b32_e32 v53, v10
	ds_read_u16 v37, v10 offset:256
	ds_read_u16 v45, v10 offset:320
	v_add_u32_e32 v6, 0x200, v6
	v_ashrrev_i32_e32 v7, 5, v6
	v_add_u32_e32 v8, v7, v153
	v_ashrrev_i32_e32 v9, 31, v8
	v_lshlrev_b64 v[8:9], 8, v[8:9]
	v_lshl_add_u64 v[8:9], v[2:3], 0, v[8:9]
	global_load_dwordx2 v[28:29], v[8:9], off
	v_mad_u64_u32 v[10:11], s[18:19], v7, s14, v[0:1]
	v_mov_b32_e32 v54, v10
	ds_read_u16 v38, v10 offset:256
	ds_read_u16 v46, v10 offset:320
	v_add_u32_e32 v6, 0x200, v6
	v_ashrrev_i32_e32 v7, 5, v6
	v_add_u32_e32 v8, v7, v153
	v_ashrrev_i32_e32 v9, 31, v8
	v_lshlrev_b64 v[8:9], 8, v[8:9]
	v_lshl_add_u64 v[8:9], v[2:3], 0, v[8:9]
	global_load_dwordx2 v[30:31], v[8:9], off
	v_mad_u64_u32 v[10:11], s[18:19], v7, s14, v[0:1]
	v_mov_b32_e32 v55, v10
	ds_read_u16 v39, v10 offset:256
	ds_read_u16 v47, v10 offset:320
	v_add_u32_e32 v6, 0x200, v6
	s_waitcnt vmcnt(0) lgkmcnt(0)
	v_lshlrev_b32_e32 v7, 16, v32
	v_lshlrev_b32_e32 v11, 16, v40
	v_mul_f32_e32 v12, v17, v11
	v_fma_f32 v12, v16, v7, -v12
	v_mul_f32_e32 v8, v16, v11
	v_fmac_f32_e32 v8, v17, v7
	v_bfe_u32 v7, v8, 16, 1
	v_add3_u32 v7, v8, v7, s22
	v_bfe_u32 v13, v12, 16, 1
	ds_write_b16_d16_hi v48, v7 offset:320
	v_add3_u32 v12, v12, v13, s22
	ds_write_b16_d16_hi v48, v12 offset:256
	v_lshlrev_b32_e32 v7, 16, v33
	v_lshlrev_b32_e32 v11, 16, v41
	v_mul_f32_e32 v12, v19, v11
	v_fma_f32 v12, v18, v7, -v12
	v_mul_f32_e32 v8, v18, v11
	v_fmac_f32_e32 v8, v19, v7
	v_bfe_u32 v7, v8, 16, 1
	v_add3_u32 v7, v8, v7, s22
	v_bfe_u32 v13, v12, 16, 1
	ds_write_b16_d16_hi v49, v7 offset:320
	v_add3_u32 v12, v12, v13, s22
	ds_write_b16_d16_hi v49, v12 offset:256
	v_lshlrev_b32_e32 v7, 16, v34
	v_lshlrev_b32_e32 v11, 16, v42
	v_mul_f32_e32 v12, v21, v11
	v_fma_f32 v12, v20, v7, -v12
	v_mul_f32_e32 v8, v20, v11
	v_fmac_f32_e32 v8, v21, v7
	v_bfe_u32 v7, v8, 16, 1
	v_add3_u32 v7, v8, v7, s22
	v_bfe_u32 v13, v12, 16, 1
	ds_write_b16_d16_hi v50, v7 offset:320
	v_add3_u32 v12, v12, v13, s22
	ds_write_b16_d16_hi v50, v12 offset:256
	v_lshlrev_b32_e32 v7, 16, v35
	v_lshlrev_b32_e32 v11, 16, v43
	v_mul_f32_e32 v12, v23, v11
	v_fma_f32 v12, v22, v7, -v12
	v_mul_f32_e32 v8, v22, v11
	v_fmac_f32_e32 v8, v23, v7
	v_bfe_u32 v7, v8, 16, 1
	v_add3_u32 v7, v8, v7, s22
	v_bfe_u32 v13, v12, 16, 1
	ds_write_b16_d16_hi v51, v7 offset:320
	v_add3_u32 v12, v12, v13, s22
	ds_write_b16_d16_hi v51, v12 offset:256
	v_lshlrev_b32_e32 v7, 16, v36
	v_lshlrev_b32_e32 v11, 16, v44
	v_mul_f32_e32 v12, v25, v11
	v_fma_f32 v12, v24, v7, -v12
	v_mul_f32_e32 v8, v24, v11
	v_fmac_f32_e32 v8, v25, v7
	v_bfe_u32 v7, v8, 16, 1
	v_add3_u32 v7, v8, v7, s22
	v_bfe_u32 v13, v12, 16, 1
	ds_write_b16_d16_hi v52, v7 offset:320
	v_add3_u32 v12, v12, v13, s22
	ds_write_b16_d16_hi v52, v12 offset:256
	v_lshlrev_b32_e32 v7, 16, v37
	v_lshlrev_b32_e32 v11, 16, v45
	v_mul_f32_e32 v12, v27, v11
	v_fma_f32 v12, v26, v7, -v12
	v_mul_f32_e32 v8, v26, v11
	v_fmac_f32_e32 v8, v27, v7
	v_bfe_u32 v7, v8, 16, 1
	v_add3_u32 v7, v8, v7, s22
	v_bfe_u32 v13, v12, 16, 1
	ds_write_b16_d16_hi v53, v7 offset:320
	v_add3_u32 v12, v12, v13, s22
	ds_write_b16_d16_hi v53, v12 offset:256
	v_lshlrev_b32_e32 v7, 16, v38
	v_lshlrev_b32_e32 v11, 16, v46
	v_mul_f32_e32 v12, v29, v11
	v_fma_f32 v12, v28, v7, -v12
	v_mul_f32_e32 v8, v28, v11
	v_fmac_f32_e32 v8, v29, v7
	v_bfe_u32 v7, v8, 16, 1
	v_add3_u32 v7, v8, v7, s22
	v_bfe_u32 v13, v12, 16, 1
	ds_write_b16_d16_hi v54, v7 offset:320
	v_add3_u32 v12, v12, v13, s22
	ds_write_b16_d16_hi v54, v12 offset:256
	v_lshlrev_b32_e32 v7, 16, v39
	v_lshlrev_b32_e32 v11, 16, v47
	v_mul_f32_e32 v12, v31, v11
	v_fma_f32 v12, v30, v7, -v12
	v_mul_f32_e32 v8, v30, v11
	v_fmac_f32_e32 v8, v31, v7
	v_bfe_u32 v7, v8, 16, 1
	v_add3_u32 v7, v8, v7, s22
	v_bfe_u32 v13, v12, 16, 1
	ds_write_b16_d16_hi v55, v7 offset:320
	v_add3_u32 v12, v12, v13, s22
	ds_write_b16_d16_hi v55, v12 offset:256

; template <int DK, int DV, int KT, bool SAMPLE>
; DI void attn_item(CP c, int l, int qb, int h, unsigned char* sm) {
;     ...
;             {
;                 constexpr int NKP = DK / 32;
;                 bf16x8 Kf[2][2 * NMT]; bf16x8 Ql[2][2];
; #pragma unroll
;                 for (int e = 0; e < 2; ++e) {
; #pragma unroll
;                     for (int mt = 0; mt < NMT; ++mt) Kf[0][e * NMT + mt] = *(const bf16x8*)(Ks + (32 * mt + l31) * QS + 16 * e + 8 * hh);
;                     if (!QREG) Ql[0][e] = *(const bf16x8*)(Qs + (32 * wq + l31) * QS + 16 * e + 8 * hh); }
; #pragma unroll
;                 for (int kp = 0; kp < NKP; ++kp) {
;                     if (kp + 1 < NKP) {
; #pragma unroll
;                         for (int e = 0; e < 2; ++e) {
; #pragma unroll
;                             for (int mt = 0; mt < NMT; ++mt) Kf[(kp + 1) & 1][e * NMT + mt] = *(const bf16x8*)(Ks + (32 * mt + l31) * QS + 16 * (2 * kp + 2 + e) + 8 * hh);
;                             if (!QREG) Ql[(kp + 1) & 1][e] = *(const bf16x8*)(Qs + (32 * wq + l31) * QS + 16 * (2 * kp + 2 + e) + 8 * hh); } }
;                     __builtin_amdgcn_sched_barrier(0);
; #pragma unroll
;                     for (int e = 0; e < 2; ++e)
; #pragma unroll
;                         for (int mt = 0; mt < NMT; ++mt) S[mt] = __builtin_amdgcn_mfma_f32_32x32x16_bf16(Kf[kp & 1][e * NMT + mt], !QREG ? Ql[kp & 1][e] : Qf[QREG ? 2 * kp + e : 0], S[mt], 0, 0, 0);
;                     __builtin_amdgcn_sched_barrier(0);
;                 }
;             }
;             float mloc = -INFINITY;
; #pragma unroll
;             for (int mt = 0; mt < NMT; ++mt)
; #pragma unroll
;                 for (int i = 0; i < 16; ++i) { float s = S[mt][i] * scale;
;                     if (SAMPLE) { const int key = kt * KT + 32 * mt + (i & 3) + 8 * (i >> 2) + 4 * hh; if (key >= 2064) s = -INFINITY; }
;                     S[mt][i] = s; mloc = fmaxf(mloc, s); }
;             mloc = fmaxf(mloc, __shfl_xor(mloc, 32));
;             const float mnew = fmaxf(m_run, mloc); const float alpha = __builtin_amdgcn_exp2f(m_run - mnew); float psum = 0.f;
; #pragma unroll
;             for (int mt = 0; mt < NMT; ++mt)
; #pragma unroll
;                 for (int i = 0; i < 16; ++i) { const float p = __builtin_amdgcn_exp2f(S[mt][i] - mnew); S[mt][i] = p; psum += p; }
;             l_run = l_run * alpha + psum; m_run = mnew;
.LBB0_649:
	s_or_b64 exec, exec, s[16:17]
	v_cmp_le_i32_e32 vcc, v80, v175
	s_and_saveexec_b64 s[16:17], vcc
	s_cbranch_execz .LBB0_646
	ds_read_b128 v[4:7], v180 offset:51200
	ds_read_b128 v[8:11], v180 offset:51232
	ds_read_b128 v[12:15], v180 offset:64000
	ds_read_b128 v[184:187], v180 offset:64032
	ds_read_b128 v[80:83], v181
	ds_read_b128 v[214:217], v181 offset:32
	ds_read_b128 v[218:221], v180 offset:51264
	ds_read_b128 v[222:225], v180 offset:51296
	ds_read_b128 v[226:229], v180 offset:64064
	ds_read_b128 v[230:233], v180 offset:64096
	ds_read_b128 v[234:237], v181 offset:64
	ds_read_b128 v[238:241], v181 offset:96
	s_waitcnt lgkmcnt(7)
	v_mfma_f32_32x32x16_bf16 v[96:111], v[4:7], v[80:83], 0
	v_mfma_f32_32x32x16_bf16 v[80:95], v[12:15], v[80:83], 0
	s_waitcnt lgkmcnt(6)
	v_mfma_f32_32x32x16_bf16 v[96:111], v[8:11], v[214:217], v[96:111]
	v_mfma_f32_32x32x16_bf16 v[80:95], v[184:187], v[214:217], v[80:95]
	ds_read_b128 v[4:7], v180 offset:51328
	ds_read_b128 v[8:11], v180 offset:51360
	ds_read_b128 v[12:15], v180 offset:64128
	ds_read_b128 v[184:187], v180 offset:64160
	ds_read_b128 v[214:217], v181 offset:128
	ds_read_b128 v[242:245], v181 offset:160
	s_waitcnt lgkmcnt(7)
	v_mfma_f32_32x32x16_bf16 v[96:111], v[218:221], v[234:237], v[96:111]
	v_mfma_f32_32x32x16_bf16 v[80:95], v[226:229], v[234:237], v[80:95]
	s_waitcnt lgkmcnt(6)
	v_mfma_f32_32x32x16_bf16 v[96:111], v[222:225], v[238:241], v[96:111]
	v_mfma_f32_32x32x16_bf16 v[80:95], v[230:233], v[238:241], v[80:95]
	ds_read_b128 v[218:221], v180 offset:51392
	ds_read_b128 v[222:225], v180 offset:51424
	ds_read_b128 v[226:229], v180 offset:64192
	ds_read_b128 v[230:233], v180 offset:64224
	ds_read_b128 v[234:237], v181 offset:192
	ds_read_b128 v[238:241], v181 offset:224
	s_waitcnt lgkmcnt(7)
	v_mfma_f32_32x32x16_bf16 v[96:111], v[4:7], v[214:217], v[96:111]
	v_mfma_f32_32x32x16_bf16 v[80:95], v[12:15], v[214:217], v[80:95]
	s_waitcnt lgkmcnt(6)
	v_mfma_f32_32x32x16_bf16 v[96:111], v[8:11], v[242:245], v[96:111]
	v_mfma_f32_32x32x16_bf16 v[80:95], v[184:187], v[242:245], v[80:95]
	ds_read_b128 v[4:7], v180 offset:51456
	ds_read_b128 v[8:11], v180 offset:51488
	ds_read_b128 v[12:15], v180 offset:64256
	ds_read_b128 v[184:187], v180 offset:64288
	ds_read_b128 v[214:217], v181 offset:256
	ds_read_b128 v[242:245], v181 offset:288
	s_waitcnt lgkmcnt(7)
	v_mfma_f32_32x32x16_bf16 v[96:111], v[218:221], v[234:237], v[96:111]
	v_mfma_f32_32x32x16_bf16 v[80:95], v[226:229], v[234:237], v[80:95]
	s_waitcnt lgkmcnt(6)
	v_mfma_f32_32x32x16_bf16 v[96:111], v[222:225], v[238:241], v[96:111]
	v_mfma_f32_32x32x16_bf16 v[80:95], v[230:233], v[238:241], v[80:95]
	ds_read_b128 v[218:221], v180 offset:51520
	ds_read_b128 v[222:225], v180 offset:51552
	ds_read_b128 v[226:229], v180 offset:64320
	ds_read_b128 v[230:233], v180 offset:64352
	ds_read_b128 v[234:237], v181 offset:320
	ds_read_b128 v[238:241], v181 offset:352
	s_waitcnt lgkmcnt(7)
	v_mfma_f32_32x32x16_bf16 v[96:111], v[4:7], v[214:217], v[96:111]
	v_mfma_f32_32x32x16_bf16 v[80:95], v[12:15], v[214:217], v[80:95]
	s_waitcnt lgkmcnt(6)
	v_mfma_f32_32x32x16_bf16 v[96:111], v[8:11], v[242:245], v[96:111]
	v_mfma_f32_32x32x16_bf16 v[80:95], v[184:187], v[242:245], v[80:95]
	s_waitcnt lgkmcnt(1)
	v_mfma_f32_32x32x16_bf16 v[96:111], v[218:221], v[234:237], v[96:111]
	v_mfma_f32_32x32x16_bf16 v[80:95], v[226:229], v[234:237], v[80:95]
	s_waitcnt lgkmcnt(0)
	v_mfma_f32_32x32x16_bf16 v[96:111], v[222:225], v[238:241], v[96:111]
	v_mfma_f32_32x32x16_bf16 v[80:95], v[230:233], v[238:241], v[80:95]
	s_nop 10
	s_mov_b32 s18, 0xff800000
	v_max3_f32 v0, v96, s18, v97
	v_max3_f32 v0, v0, v98, v99
	v_max3_f32 v0, v0, v100, v101
	v_max3_f32 v0, v0, v102, v103
	v_max3_f32 v0, v0, v104, v105
	v_max3_f32 v0, v0, v106, v107
	v_max3_f32 v0, v0, v108, v109
	v_max3_f32 v0, v0, v110, v111
	v_max3_f32 v0, v0, v80, v81
	v_max3_f32 v0, v0, v82, v83
	v_max3_f32 v0, v0, v84, v85
	v_max3_f32 v0, v0, v86, v87
	v_max3_f32 v0, v0, v88, v89
	v_max3_f32 v0, v0, v90, v91
	v_max3_f32 v0, v0, v92, v93
	v_max3_f32 v0, v0, v94, v95
	s_mov_b32 s18, 0x3dd53b94
	v_mul_f32_e32 v0, 0x3dd53b94, v0
	v_add_u32_e32 v226, 0x6000, v182
	v_mov_b32_e32 v3, v0
	v_mov_b32_e32 v4, v0
	v_add_u32_e32 v227, 0x7000, v182
	v_add_u32_e32 v228, 0x8800, v182
	v_permlane32_swap_b32_e32 v3, v4
	v_add_u32_e32 v229, 0x9800, v182
	v_max3_f32 v3, v183, v3, v4
	v_fma_f32 v4, v96, s18, -v3
	v_sub_f32_e32 v0, v183, v3
	v_exp_f32_e32 v183, v4
	v_fma_f32 v4, v97, s18, -v3
	v_exp_f32_e32 v184, v4
	v_fma_f32 v4, v98, s18, -v3
	v_exp_f32_e32 v185, v4
	v_fma_f32 v4, v99, s18, -v3
	v_exp_f32_e32 v186, v4
	v_fma_f32 v5, v100, s18, -v3
	v_add_f32_e32 v4, 0, v183
	v_exp_f32_e32 v187, v5
	v_fma_f32 v5, v101, s18, -v3
	v_add_f32_e32 v4, v184, v4
	v_exp_f32_e32 v192, v5
	v_fma_f32 v5, v102, s18, -v3
	v_add_f32_e32 v4, v185, v4
	v_exp_f32_e32 v193, v5
	v_fma_f32 v5, v103, s18, -v3
	v_add_f32_e32 v4, v186, v4
	v_exp_f32_e32 v103, v5
	v_fma_f32 v5, v104, s18, -v3
	v_add_f32_e32 v4, v187, v4
	v_exp_f32_e32 v104, v5
	v_fma_f32 v5, v105, s18, -v3
	v_add_f32_e32 v4, v192, v4
	v_exp_f32_e32 v105, v5
	v_fma_f32 v5, v106, s18, -v3
	v_add_f32_e32 v4, v193, v4
	v_exp_f32_e32 v106, v5
	v_fma_f32 v5, v107, s18, -v3
	v_add_f32_e32 v4, v103, v4
	v_exp_f32_e32 v107, v5
	v_fma_f32 v5, v108, s18, -v3
	v_add_f32_e32 v4, v104, v4
	v_exp_f32_e32 v108, v5
	v_fma_f32 v5, v109, s18, -v3
	v_add_f32_e32 v4, v105, v4
	v_exp_f32_e32 v109, v5
	v_fma_f32 v5, v110, s18, -v3
	v_add_f32_e32 v4, v106, v4
	v_exp_f32_e32 v110, v5
	v_fma_f32 v5, v111, s18, -v3
	v_add_f32_e32 v4, v107, v4
	v_exp_f32_e32 v111, v5
	v_fma_f32 v5, v80, s18, -v3
	v_add_f32_e32 v4, v108, v4
; DI unsigned pk2(float lo, float hi) { const hwf2_t v = {lo, hi}; const hwbf2_t b = __builtin_convertvector(v, hwbf2_t); return __builtin_bit_cast(unsigned, b); }
; #define ATT_LDV(buf, gi) do { const int _kg = (gi) / NDB, _db = (gi) % NDB; _Pragma("unroll") for (int d = 0; d < 4; ++d) { const bf16_t* vp = Vs + (32 * (4 * _db + d) + l31) * VS + 16 * _kg + 4 * hh; \
;                         const u32x2 lo = *(const u32x2*)vp, hi = *(const u32x2*)(vp + 8); Vf[buf][d].x = lo.x; Vf[buf][d].y = lo.y; Vf[buf][d].z = hi.x; Vf[buf][d].w = hi.y; } } while (0)
; template <int DK, int DV, int KT, bool SAMPLE>
; DI void attn_item(CP c, int l, int qb, int h, unsigned char* sm) {
;     ...
;             const float mnew = fmaxf(m_run, mloc); const float alpha = __builtin_amdgcn_exp2f(m_run - mnew); float psum = 0.f;
; #pragma unroll
;             for (int mt = 0; mt < NMT; ++mt)
; #pragma unroll
;                 for (int i = 0; i < 16; ++i) { const float p = __builtin_amdgcn_exp2f(S[mt][i] - mnew); S[mt][i] = p; psum += p; }
;             l_run = l_run * alpha + psum; m_run = mnew;
; #pragma unroll
;             for (int d = 0; d < NDT; ++d) Oacc[d] = Oacc[d] * alpha;
;             {
;                 constexpr int NDB = NDT / 4;
;                 constexpr int NG = 2 * NMT * NDB;
;                 u32x4 Vf[2][4];
;     ...
;                 ATT_LDV(0, 0);
; #pragma unroll
;                 for (int gi = 0; gi < NG; ++gi) { const int kg = gi / NDB, db = gi % NDB, mt = kg >> 1, s2 = kg & 1;
;                     if (gi + 1 < NG) ATT_LDV((gi + 1) & 1, gi + 1);
;                     u32x4 pw; pw.x = pk2(S[mt][8 * s2 + 0], S[mt][8 * s2 + 1]); pw.y = pk2(S[mt][8 * s2 + 2], S[mt][8 * s2 + 3]);
;                     pw.z = pk2(S[mt][8 * s2 + 4], S[mt][8 * s2 + 5]); pw.w = pk2(S[mt][8 * s2 + 6], S[mt][8 * s2 + 7]);
;                     const bf16x8 pf = __builtin_bit_cast(bf16x8, pw);
;                     __builtin_amdgcn_sched_barrier(0);
; #pragma unroll
;                     for (int d = 0; d < 4; ++d) Oacc[4 * db + d] = __builtin_amdgcn_mfma_f32_32x32x16_bf16(__builtin_bit_cast(bf16x8, Vf[gi & 1][d]), pf, Oacc[4 * db + d], 0, 0, 0);
;                     __builtin_amdgcn_sched_barrier(0);
;                 }
	v_exp_f32_e32 v204, v5
	v_fma_f32 v5, v81, s18, -v3
	v_add_f32_e32 v4, v109, v4
	v_exp_f32_e32 v205, v5
	v_fma_f32 v5, v82, s18, -v3
	v_add_f32_e32 v4, v110, v4
	v_exp_f32_e32 v206, v5
	v_fma_f32 v5, v83, s18, -v3
	v_add_f32_e32 v4, v111, v4
	v_exp_f32_e32 v207, v5
	v_fma_f32 v5, v84, s18, -v3
	v_exp_f32_e32 v213, v5
	v_fma_f32 v5, v85, s18, -v3
	v_add_f32_e32 v4, v204, v4
	v_exp_f32_e32 v214, v5
	v_fma_f32 v5, v86, s18, -v3
	v_add_f32_e32 v4, v205, v4
	v_exp_f32_e32 v215, v5
	v_fma_f32 v5, v87, s18, -v3
	v_add_f32_e32 v4, v206, v4
	v_exp_f32_e32 v216, v5
	v_fma_f32 v5, v88, s18, -v3
	v_add_f32_e32 v4, v207, v4
	v_exp_f32_e32 v217, v5
	v_fma_f32 v5, v89, s18, -v3
	v_add_f32_e32 v4, v213, v4
	v_exp_f32_e32 v218, v5
	v_fma_f32 v5, v90, s18, -v3
	v_add_f32_e32 v4, v214, v4
	v_exp_f32_e32 v219, v5
	v_fma_f32 v5, v91, s18, -v3
	v_add_f32_e32 v4, v215, v4
	v_exp_f32_e32 v220, v5
	v_fma_f32 v5, v92, s18, -v3
	v_add_f32_e32 v4, v216, v4
	v_exp_f32_e32 v221, v5
	v_fma_f32 v5, v93, s18, -v3
	v_add_f32_e32 v4, v217, v4
	v_exp_f32_e32 v222, v5
	v_fma_f32 v5, v94, s18, -v3
	v_add_f32_e32 v4, v218, v4
	v_exp_f32_e32 v223, v5
	v_fma_f32 v5, v95, s18, -v3
	v_add_f32_e32 v4, v219, v4
	v_exp_f32_e32 v224, v5
	v_add_f32_e32 v4, v220, v4
	v_add_f32_e32 v4, v221, v4
	v_add_f32_e32 v4, v222, v4
	v_add_f32_e32 v4, v223, v4
	v_add_f32_e32 v225, v224, v4
	ds_read2_b64 v[4:7], v226 offset0:128 offset1:130
	ds_read2_b64 v[8:11], v226 offset0:132 offset1:134
	ds_read2_b64 v[12:15], v227 offset0:192 offset1:194
	ds_read2_b64 v[80:83], v228 offset1:2
	ds_read2_b64 v[84:87], v229 offset0:64 offset1:66
	ds_read2_b64 v[88:91], v227 offset0:196 offset1:198
	ds_read2_b64 v[92:95], v228 offset0:4 offset1:6
	ds_read2_b64 v[96:99], v229 offset0:68 offset1:70
	v_exp_f32_e32 v0, v0
	v_cvt_pk_bf16_f32 v100, v183, v184
	v_cvt_pk_bf16_f32 v101, v185, v186
	v_cvt_pk_bf16_f32 v102, v187, v192
	v_pk_mul_f32 v[78:79], v[78:79], v[0:1] op_sel_hi:[1,0]
	v_pk_mul_f32 v[76:77], v[76:77], v[0:1] op_sel_hi:[1,0]
	v_pk_mul_f32 v[74:75], v[74:75], v[0:1] op_sel_hi:[1,0]
	v_pk_mul_f32 v[72:73], v[72:73], v[0:1] op_sel_hi:[1,0]
	v_pk_mul_f32 v[70:71], v[70:71], v[0:1] op_sel_hi:[1,0]
	v_pk_mul_f32 v[68:69], v[68:69], v[0:1] op_sel_hi:[1,0]
	v_pk_mul_f32 v[66:67], v[66:67], v[0:1] op_sel_hi:[1,0]
	v_pk_mul_f32 v[64:65], v[64:65], v[0:1] op_sel_hi:[1,0]
	v_pk_mul_f32 v[62:63], v[62:63], v[0:1] op_sel_hi:[1,0]
	v_pk_mul_f32 v[60:61], v[60:61], v[0:1] op_sel_hi:[1,0]
	v_pk_mul_f32 v[58:59], v[58:59], v[0:1] op_sel_hi:[1,0]
	v_pk_mul_f32 v[56:57], v[56:57], v[0:1] op_sel_hi:[1,0]
	v_pk_mul_f32 v[54:55], v[54:55], v[0:1] op_sel_hi:[1,0]
	v_pk_mul_f32 v[52:53], v[52:53], v[0:1] op_sel_hi:[1,0]
	v_pk_mul_f32 v[50:51], v[50:51], v[0:1] op_sel_hi:[1,0]
	v_pk_mul_f32 v[48:49], v[48:49], v[0:1] op_sel_hi:[1,0]
	v_pk_mul_f32 v[46:47], v[46:47], v[0:1] op_sel_hi:[1,0]
	v_pk_mul_f32 v[44:45], v[44:45], v[0:1] op_sel_hi:[1,0]
	v_pk_mul_f32 v[42:43], v[42:43], v[0:1] op_sel_hi:[1,0]
	v_pk_mul_f32 v[40:41], v[40:41], v[0:1] op_sel_hi:[1,0]
	v_pk_mul_f32 v[38:39], v[38:39], v[0:1] op_sel_hi:[1,0]
	v_pk_mul_f32 v[36:37], v[36:37], v[0:1] op_sel_hi:[1,0]
	v_pk_mul_f32 v[34:35], v[34:35], v[0:1] op_sel_hi:[1,0]
	v_pk_mul_f32 v[32:33], v[32:33], v[0:1] op_sel_hi:[1,0]
	v_pk_mul_f32 v[30:31], v[30:31], v[0:1] op_sel_hi:[1,0]
	v_pk_mul_f32 v[28:29], v[28:29], v[0:1] op_sel_hi:[1,0]
	v_pk_mul_f32 v[26:27], v[26:27], v[0:1] op_sel_hi:[1,0]
	v_pk_mul_f32 v[24:25], v[24:25], v[0:1] op_sel_hi:[1,0]
	v_pk_mul_f32 v[22:23], v[22:23], v[0:1] op_sel_hi:[1,0]
	v_pk_mul_f32 v[20:21], v[20:21], v[0:1] op_sel_hi:[1,0]
	v_pk_mul_f32 v[18:19], v[18:19], v[0:1] op_sel_hi:[1,0]
	v_pk_mul_f32 v[16:17], v[16:17], v[0:1] op_sel_hi:[1,0]
	v_cvt_pk_bf16_f32 v103, v193, v103
	s_waitcnt lgkmcnt(7)
	s_nop 0
	v_mfma_f32_32x32x16_bf16 v[64:79], v[4:7], v[100:103], v[64:79]
	s_waitcnt lgkmcnt(5)
	v_mfma_f32_32x32x16_bf16 v[48:63], v[12:15], v[100:103], v[48:63]
	s_waitcnt lgkmcnt(4)
	v_mfma_f32_32x32x16_bf16 v[32:47], v[80:83], v[100:103], v[32:47]
	s_waitcnt lgkmcnt(3)
	v_mfma_f32_32x32x16_bf16 v[16:31], v[84:87], v[100:103], v[16:31]
	ds_read2_b64 v[4:7], v226 offset0:136 offset1:138
	ds_read2_b64 v[12:15], v227 offset0:200 offset1:202
	ds_read2_b64 v[80:83], v228 offset0:8 offset1:10
	ds_read2_b64 v[84:87], v229 offset0:72 offset1:74
	v_cvt_pk_bf16_f32 v100, v104, v105
	v_cvt_pk_bf16_f32 v101, v106, v107
	v_cvt_pk_bf16_f32 v102, v108, v109
	v_cvt_pk_bf16_f32 v103, v110, v111
	s_nop 1
	v_mfma_f32_32x32x16_bf16 v[64:79], v[8:11], v[100:103], v[64:79]
	s_waitcnt lgkmcnt(6)
	v_mfma_f32_32x32x16_bf16 v[48:63], v[88:91], v[100:103], v[48:63]
	s_waitcnt lgkmcnt(5)
	v_mfma_f32_32x32x16_bf16 v[32:47], v[92:95], v[100:103], v[32:47]
	s_waitcnt lgkmcnt(4)
	v_mfma_f32_32x32x16_bf16 v[16:31], v[96:99], v[100:103], v[16:31]
	ds_read2_b64 v[8:11], v226 offset0:140 offset1:142
	ds_read2_b64 v[88:91], v227 offset0:204 offset1:206
	ds_read2_b64 v[92:95], v228 offset0:12 offset1:14
	ds_read2_b64 v[96:99], v229 offset0:76 offset1:78
	v_cvt_pk_bf16_f32 v100, v204, v205
	v_cvt_pk_bf16_f32 v101, v206, v207
	v_cvt_pk_bf16_f32 v102, v213, v214
	v_cvt_pk_bf16_f32 v103, v215, v216
	s_waitcnt lgkmcnt(7)
	s_nop 0
	v_mfma_f32_32x32x16_bf16 v[64:79], v[4:7], v[100:103], v[64:79]
	s_waitcnt lgkmcnt(6)
	v_mfma_f32_32x32x16_bf16 v[48:63], v[12:15], v[100:103], v[48:63]
	s_waitcnt lgkmcnt(5)
	v_mfma_f32_32x32x16_bf16 v[32:47], v[80:83], v[100:103], v[32:47]
	s_waitcnt lgkmcnt(4)
	v_mfma_f32_32x32x16_bf16 v[16:31], v[84:87], v[100:103], v[16:31]
	v_cvt_pk_bf16_f32 v4, v217, v218
	v_cvt_pk_bf16_f32 v5, v219, v220
	v_cvt_pk_bf16_f32 v6, v221, v222
	v_cvt_pk_bf16_f32 v7, v223, v224
	s_waitcnt lgkmcnt(3)
	s_nop 0
	v_mfma_f32_32x32x16_bf16 v[64:79], v[8:11], v[4:7], v[64:79]
	s_waitcnt lgkmcnt(2)
	v_mfma_f32_32x32x16_bf16 v[48:63], v[88:91], v[4:7], v[48:63]
	s_waitcnt lgkmcnt(1)
	v_mfma_f32_32x32x16_bf16 v[32:47], v[92:95], v[4:7], v[32:47]
	s_waitcnt lgkmcnt(0)
	v_mfma_f32_32x32x16_bf16 v[16:31], v[96:99], v[4:7], v[16:31]
	v_fmac_f32_e32 v225, v177, v0
	v_mov_b32_e32 v177, v225
	v_mov_b32_e32 v183, v3
	s_branch .LBB0_646
